# attention phase: static s_setprio 1 on the leading virtual block (waves 0-3) instead of the trailing one (per-half comparison)
# speedup vs baseline: 1.0034x; 1.0006x over previous
; DI int bidx() { int t = __builtin_amdgcn_readfirstlane((int)(blockIdx.x * 2 + (threadIdx.x >> 8))); asm volatile("" : "+s"(t)); return t; }
; DI int gdim() { int t = gridDim.x * 2; asm volatile("" : "+s"(t)); return t; }
; DI void phase_attn(KargPtr p, unsigned char* smem) {
;     for (int idx = bidx(); idx < 6144; idx += gdim()) {
;         if (idx < 4096) {
;             const int j = idx >> 9, g = (idx >> 7) & 3, rem = idx & 127, bh = ((rem & 63) + 13 * j) & 63;
;             const int qb = 31 - 4 * j - ((j & 1) ? 3 - g : g);
;             const int type = ((rem >> 6) + j) & 1;
;             if (type == 0) attn_item<0>(p, bh >> 3, bh & 7, qb, smem);
;             else attn_item<1>(p, bh >> 3, bh & 7, qb, smem);
;         } else {
;             const int j = idx - 4096; const int qb = 31 - (j >> 6), bh = j & 63;
;             attn_item<2>(p, bh >> 3, bh & 7, qb, smem);
;         }
;     }
; }
.LBB0_562:
	s_and_b64 vcc, exec, s[4:5]
	s_cbranch_vccz .LBB0_631
	s_cmp_lg_u32 s3, 0
	s_cbranch_scc1 .Lattn_noprio
	s_setprio 1
